# sel loop fast path reads raw QK scores directly (no masked copies), exp/cvt interleaved with PV MFMAs per 8-key group
# baseline (speedup 1.0000x reference)
; __device__ __forceinline__ int crow(int r, int hi) { return (r & 3) + 8 * (r >> 2) + 4 * hi; }
; template <bool WITH_O>
; __device__ __forceinline__ void softmax_step(float& m, float& l, f32x16 (&o)[4], f32x16& p0, f32x16& p1, LAS float* wsf, int r32, int hi) {
;     float mxa = fmaxf(fmaxf(p0[0], p1[0]), p0[1]), mxb = fmaxf(fmaxf(p1[1], p0[2]), p1[2]);
; #pragma unroll
;     for (int r = 3; r < 15; r += 2) { mxa = fmaxf(fmaxf(mxa, p0[r]), p1[r]); mxb = fmaxf(fmaxf(mxb, p0[r + 1]), p1[r + 1]); }
;     float mx = fmaxf(fmaxf(mxa, mxb), fmaxf(p0[15], p1[15]));
;     mx = fmaxf(mx, __shfl_xor(mx, 32));
;     const bool grow = __any(mx > m + 8.f);
;     const float mnew = grow ? fmaxf(m, mx) : m;
;     const float f = grow ? __builtin_amdgcn_exp2f(m - mnew) : 1.f;
;     m = mnew;
;     float s = 0.f;
; #pragma unroll
;     for (int r = 0; r < 16; ++r) { p0[r] = __builtin_amdgcn_exp2f(p0[r] - mnew); p1[r] = __builtin_amdgcn_exp2f(p1[r] - mnew); s += p0[r] + p1[r]; }
;     l = l * f + s;
;     if (WITH_O) {
;         if (grow) {
;             if (hi == 0) wsf[r32] = f;
;             asm volatile("s_waitcnt lgkmcnt(0)" ::: "memory");
; #pragma unroll
;             for (int r = 0; r < 16; ++r) { const float fr = wsf[crow(r, hi)];
; #pragma unroll
;                 for (int db = 0; db < 4; ++db) o[db][r] *= fr; }
; __device__ __forceinline__ void nsa_unit(int hk, int T, LAS unsigned char* lds, LAS float* wsf, const AttnPtrs& P) {
;     ...
;                 const unsigned mw = sel[(8 * w + qi) * 8 + (j >> 5)];
;                 const bool mine = (mw >> (j & 31)) & 1u;
; #pragma unroll
;                 for (int r = 0; r < 16; ++r) { const int key = 64 * j + crow(r, hi);
;                     if (!mine || key > tq) p0[r] = -INFINITY; if (!mine || key + 32 > tq) p1[r] = -INFINITY; }
;                 softmax_step<true>(m, l, o, p0, p1, wsf, r32, hi);
.LBB0_1458:
	s_lshr_b32 s6, s11, 5
	s_lshl_b32 s8, 1, s11
	v_readlane_b32 s9, v253, s6
	s_and_b32 s9, s9, s8
	s_cmp_eq_u32 s9, 0
	s_cbranch_scc1 .LBB0_1464
	s_mul_i32 s7, s7, 0x8c00
	s_add_i32 s12, s7, 0
	v_add3_u32 v0, s12, v195, v166
	v_lshl_add_u32 v254, s6, 2, v196
	ds_read_b32 v254, v254
	ds_read_b128 v[2:5], v0
	ds_read_b128 v[6:9], v0 offset:32
	ds_read_b128 v[10:13], v0 offset:8704
	ds_read_b128 v[202:205], v0 offset:8736
	s_waitcnt lgkmcnt(3)
	v_mfma_f32_32x32x16_bf16 v[96:111], v[2:5], v[112:115], 0
	ds_read_b128 v[2:5], v0 offset:64
	ds_read_b128 v[206:209], v0 offset:8768
	s_waitcnt lgkmcnt(3)
	v_mfma_f32_32x32x16_bf16 v[64:79], v[10:13], v[112:115], 0
	v_mfma_f32_32x32x16_bf16 v[96:111], v[6:9], v[116:119], v[96:111]
	ds_read_b128 v[6:9], v0 offset:96
	ds_read_b128 v[10:13], v0 offset:8800
	s_waitcnt lgkmcnt(4)
	v_mfma_f32_32x32x16_bf16 v[64:79], v[202:205], v[116:119], v[64:79]
	s_waitcnt lgkmcnt(3)
	v_mfma_f32_32x32x16_bf16 v[96:111], v[2:5], v[120:123], v[96:111]
	ds_read_b128 v[2:5], v0 offset:128
	ds_read_b128 v[202:205], v0 offset:8832
	s_waitcnt lgkmcnt(4)
	v_mfma_f32_32x32x16_bf16 v[64:79], v[206:209], v[120:123], v[64:79]
	s_waitcnt lgkmcnt(3)
	v_mfma_f32_32x32x16_bf16 v[96:111], v[6:9], v[124:127], v[96:111]
	ds_read_b128 v[6:9], v0 offset:160
	ds_read_b128 v[206:209], v0 offset:8864
	s_waitcnt lgkmcnt(4)
	v_mfma_f32_32x32x16_bf16 v[64:79], v[10:13], v[124:127], v[64:79]
	s_waitcnt lgkmcnt(3)
	v_mfma_f32_32x32x16_bf16 v[96:111], v[2:5], v[128:131], v[96:111]
	ds_read_b128 v[2:5], v0 offset:192
	ds_read_b128 v[10:13], v0 offset:8896
	s_waitcnt lgkmcnt(4)
	v_mfma_f32_32x32x16_bf16 v[64:79], v[202:205], v[128:131], v[64:79]
	s_waitcnt lgkmcnt(3)
	v_mfma_f32_32x32x16_bf16 v[96:111], v[6:9], v[132:135], v[96:111]
	ds_read_b128 v[6:9], v0 offset:224
	ds_read_b128 v[202:205], v0 offset:8928
	s_waitcnt lgkmcnt(4)
	v_mfma_f32_32x32x16_bf16 v[64:79], v[206:209], v[132:135], v[64:79]
	s_waitcnt lgkmcnt(3)
	v_mfma_f32_32x32x16_bf16 v[96:111], v[2:5], v[136:139], v[96:111]
	s_waitcnt lgkmcnt(2)
	v_mfma_f32_32x32x16_bf16 v[64:79], v[10:13], v[136:139], v[64:79]
	s_waitcnt lgkmcnt(1)
	v_mfma_f32_32x32x16_bf16 v[96:111], v[6:9], v[140:143], v[96:111]
	s_waitcnt lgkmcnt(0)
	v_mfma_f32_32x32x16_bf16 v[64:79], v[202:205], v[140:143], v[64:79]
	v_and_b32_e32 v0, s8, v254
	v_cmp_eq_u32_e32 vcc, 0, v0
	s_cmp_eq_u32 s11, s97
	s_cbranch_scc1 .Lsel_lastmask
	s_mov_b64 s[98:99], vcc
	s_nop 6
	v_max3_f32 v2, v96, v64, v97
	v_max3_f32 v3, v65, v98, v66
	v_max3_f32 v2, v2, v99, v67
	v_max3_f32 v3, v3, v100, v68
	v_max3_f32 v2, v2, v101, v69
	v_max3_f32 v3, v3, v102, v70
	v_max3_f32 v2, v2, v103, v71
	v_max3_f32 v3, v3, v104, v72
	v_max3_f32 v2, v2, v105, v73
	v_max3_f32 v3, v3, v106, v74
	v_max3_f32 v2, v2, v107, v75
	v_max3_f32 v3, v3, v108, v76
	v_max3_f32 v2, v2, v109, v77
	v_max3_f32 v3, v3, v110, v78
	v_max3_f32 v2, v2, v111, v79
	v_max_f32_e32 v2, v2, v3
	v_cndmask_b32_e64 v2, v2, v185, s[98:99]
	ds_bpermute_b32 v3, v188, v2
	s_waitcnt lgkmcnt(0)
	v_max_f32_e32 v3, v3, v3
	v_max_f32_e32 v2, v2, v3
	v_add_f32_e32 v3, 0x41000000, v200
	v_cmp_gt_f32_e32 vcc, v2, v3
	s_cmp_eq_u64 vcc, 0
	v_max_f32_e32 v3, v200, v200
	v_max_f32_e32 v0, v3, v2
	s_cselect_b64 s[6:7], -1, 0
	v_cndmask_b32_e64 v0, v0, v200, s[6:7]
	v_sub_f32_e32 v14, v200, v0
	v_exp_f32_e32 v14, v14
	v_mov_b32_e32 v15, 0x7f800000
	v_cndmask_b32_e64 v15, v0, v15, s[98:99]
	s_and_b64 vcc, exec, s[6:7]
	s_cbranch_vccnz .Lsel_f_nogrow
	s_and_saveexec_b64 s[8:9], s[4:5]
	ds_write_b32 v192, v14
	s_or_b64 exec, exec, s[8:9]
	s_waitcnt lgkmcnt(0)
	ds_read_b128 v[2:5], v193 offset:96
	ds_read_b128 v[6:9], v193 offset:64
	ds_read_b128 v[10:13], v193 offset:32
	ds_read_b128 v[202:205], v193
	s_waitcnt lgkmcnt(3)
	v_pk_mul_f32 v[60:61], v[60:61], v[2:3]
	s_waitcnt lgkmcnt(2)
	v_pk_mul_f32 v[56:57], v[56:57], v[6:7]
	s_waitcnt lgkmcnt(1)
	v_pk_mul_f32 v[52:53], v[52:53], v[10:11]
	v_pk_mul_f32 v[62:63], v[62:63], v[4:5]
	v_pk_mul_f32 v[58:59], v[58:59], v[8:9]
	v_pk_mul_f32 v[54:55], v[54:55], v[12:13]
	s_waitcnt lgkmcnt(0)
	v_pk_mul_f32 v[50:51], v[50:51], v[204:205]
	v_pk_mul_f32 v[48:49], v[48:49], v[202:203]
	v_pk_mul_f32 v[44:45], v[44:45], v[2:3]
	v_pk_mul_f32 v[40:41], v[40:41], v[6:7]
	v_pk_mul_f32 v[36:37], v[36:37], v[10:11]
	v_pk_mul_f32 v[46:47], v[46:47], v[4:5]
	v_pk_mul_f32 v[42:43], v[42:43], v[8:9]
	v_pk_mul_f32 v[38:39], v[38:39], v[12:13]
	v_pk_mul_f32 v[34:35], v[34:35], v[204:205]
	v_pk_mul_f32 v[32:33], v[32:33], v[202:203]
	v_pk_mul_f32 v[28:29], v[28:29], v[2:3]
	v_pk_mul_f32 v[24:25], v[24:25], v[6:7]
	v_pk_mul_f32 v[20:21], v[20:21], v[10:11]
	v_pk_mul_f32 v[30:31], v[30:31], v[4:5]
	v_pk_mul_f32 v[26:27], v[26:27], v[8:9]
	v_pk_mul_f32 v[22:23], v[22:23], v[12:13]
	v_pk_mul_f32 v[18:19], v[18:19], v[204:205]
	v_pk_mul_f32 v[16:17], v[16:17], v[202:203]
	v_pk_mul_f32 v[92:93], v[92:93], v[2:3]
	v_pk_mul_f32 v[88:89], v[88:89], v[6:7]
	v_pk_mul_f32 v[84:85], v[84:85], v[10:11]
	v_pk_mul_f32 v[94:95], v[94:95], v[4:5]
	v_pk_mul_f32 v[90:91], v[90:91], v[8:9]
	v_pk_mul_f32 v[86:87], v[86:87], v[12:13]
	v_pk_mul_f32 v[82:83], v[82:83], v[204:205]
	v_pk_mul_f32 v[80:81], v[80:81], v[202:203]
; #define LAS __attribute__((address_space(3)))
; __device__ __forceinline__ unsigned pk2(float lo, float hi) { f32x2 v = {lo, hi}; bf16x2_t b = __builtin_convertvector(v, bf16x2_t); return __builtin_bit_cast(unsigned, b); }
; #define PV_LD(i_) do { vf[(i_) & 3] = *(const LAS bf16x8*)(vb2 + ((i_) & 3) * 32 * VRS + ((i_) >> 2) * 32); } while (0)
; __device__ __forceinline__ void pv_tile(f32x16 (&o)[4], const f32x16& p0, const f32x16& p1, const LAS unsigned char* Vt, int r32, int hi) {
;     bf16x8 pa[4];
; #pragma unroll
;     for (int s = 0; s < 4; ++s) { const int b = 8 * (s & 1); u32x4 w;
;         if (s < 2) { w.x = pk2(p0[b], p0[b + 1]); w.y = pk2(p0[b + 2], p0[b + 3]); w.z = pk2(p0[b + 4], p0[b + 5]); w.w = pk2(p0[b + 6], p0[b + 7]); }
;         else { w.x = pk2(p1[b], p1[b + 1]); w.y = pk2(p1[b + 2], p1[b + 3]); w.z = pk2(p1[b + 4], p1[b + 5]); w.w = pk2(p1[b + 6], p1[b + 7]); }
;         pa[s] = __builtin_bit_cast(bf16x8, w); }
;     const LAS unsigned char* vb2 = Vt + r32 * VRS + hi * 16;
;     bf16x8 vf[4];
;     ...
;     PV_LD(0); PV_LD(1); PV_LD(2);
;     __builtin_amdgcn_sched_barrier(0);
; #pragma unroll
;     for (int i = 0; i < 16; ++i) {
;         if (i + 3 < 16) PV_LD(i + 3);
;         o[i & 3] = __builtin_amdgcn_mfma_f32_32x32x16_bf16(pa[i >> 2], vf[i & 3], o[i & 3], 0, 0, 0);
;         __builtin_amdgcn_sched_barrier(0);
;     }
; template <bool WITH_O>
; __device__ __forceinline__ void softmax_step(float& m, float& l, f32x16 (&o)[4], f32x16& p0, f32x16& p1, LAS float* wsf, int r32, int hi) {
;     ...
;     for (int r = 0; r < 16; ++r) { p0[r] = __builtin_amdgcn_exp2f(p0[r] - mnew); p1[r] = __builtin_amdgcn_exp2f(p1[r] - mnew); s += p0[r] + p1[r]; }
;     l = l * f + s;
.Lsel_f_nogrow:
	v_add3_u32 v201, s12, v198, v166
	ds_read_b128 v[2:5], v201 offset:17408
	ds_read_b128 v[6:9], v201 offset:22016
	ds_read_b128 v[10:13], v201 offset:26624
	v_sub_f32_e32 v96, v96, v15
	v_sub_f32_e32 v97, v97, v15
	v_sub_f32_e32 v98, v98, v15
	v_sub_f32_e32 v99, v99, v15
	v_sub_f32_e32 v100, v100, v15
	v_sub_f32_e32 v101, v101, v15
	v_sub_f32_e32 v102, v102, v15
	v_sub_f32_e32 v103, v103, v15
	v_exp_f32_e32 v96, v96
	v_exp_f32_e32 v97, v97
	v_exp_f32_e32 v98, v98
	v_exp_f32_e32 v99, v99
	v_exp_f32_e32 v100, v100
	v_exp_f32_e32 v101, v101
	v_exp_f32_e32 v102, v102
	v_exp_f32_e32 v103, v103
	v_add_f32_e32 v200, v96, v97
	v_add_f32_e32 v200, v200, v98
	v_add_f32_e32 v200, v200, v99
	v_add_f32_e32 v200, v200, v100
	v_add_f32_e32 v200, v200, v101
	v_add_f32_e32 v200, v200, v102
	v_add_f32_e32 v200, v200, v103
	v_cvt_pk_bf16_f32 v202, v96, v97
	v_cvt_pk_bf16_f32 v203, v98, v99
	v_cvt_pk_bf16_f32 v204, v100, v101
	v_cvt_pk_bf16_f32 v205, v102, v103
	s_nop 1
	s_waitcnt lgkmcnt(2)
	v_mfma_f32_32x32x16_bf16 v[48:63], v[202:205], v[2:5], v[48:63]
	ds_read_b128 v[2:5], v201 offset:31232
	s_waitcnt lgkmcnt(2)
	v_mfma_f32_32x32x16_bf16 v[32:47], v[202:205], v[6:9], v[32:47]
	ds_read_b128 v[6:9], v201 offset:17440
	s_waitcnt lgkmcnt(2)
	v_mfma_f32_32x32x16_bf16 v[16:31], v[202:205], v[10:13], v[16:31]
	ds_read_b128 v[10:13], v201 offset:22048
	s_waitcnt lgkmcnt(2)
	v_mfma_f32_32x32x16_bf16 v[80:95], v[202:205], v[2:5], v[80:95]
	ds_read_b128 v[2:5], v201 offset:26656
	v_sub_f32_e32 v104, v104, v15
	v_sub_f32_e32 v105, v105, v15
	v_sub_f32_e32 v106, v106, v15
	v_sub_f32_e32 v107, v107, v15
	v_sub_f32_e32 v108, v108, v15
	v_sub_f32_e32 v109, v109, v15
	v_sub_f32_e32 v110, v110, v15
	v_sub_f32_e32 v111, v111, v15
	v_exp_f32_e32 v104, v104
	v_exp_f32_e32 v105, v105
	v_exp_f32_e32 v106, v106
	v_exp_f32_e32 v107, v107
	v_exp_f32_e32 v108, v108
	v_exp_f32_e32 v109, v109
	v_exp_f32_e32 v110, v110
	v_exp_f32_e32 v111, v111
	v_add_f32_e32 v200, v200, v104
	v_add_f32_e32 v200, v200, v105
	v_add_f32_e32 v200, v200, v106
	v_add_f32_e32 v200, v200, v107
	v_add_f32_e32 v200, v200, v108
	v_add_f32_e32 v200, v200, v109
	v_add_f32_e32 v200, v200, v110
	v_add_f32_e32 v200, v200, v111
	v_cvt_pk_bf16_f32 v206, v104, v105
	v_cvt_pk_bf16_f32 v207, v106, v107
	v_cvt_pk_bf16_f32 v208, v108, v109
	v_cvt_pk_bf16_f32 v209, v110, v111
	s_nop 1
	s_waitcnt lgkmcnt(2)
	v_mfma_f32_32x32x16_bf16 v[48:63], v[206:209], v[6:9], v[48:63]
	ds_read_b128 v[6:9], v201 offset:31264
	s_waitcnt lgkmcnt(2)
	v_mfma_f32_32x32x16_bf16 v[32:47], v[206:209], v[10:13], v[32:47]
	ds_read_b128 v[10:13], v201 offset:17472
	s_waitcnt lgkmcnt(2)
	v_mfma_f32_32x32x16_bf16 v[16:31], v[206:209], v[2:5], v[16:31]
	ds_read_b128 v[2:5], v201 offset:22080
	s_waitcnt lgkmcnt(2)
	v_mfma_f32_32x32x16_bf16 v[80:95], v[206:209], v[6:9], v[80:95]
	ds_read_b128 v[6:9], v201 offset:26688
	v_sub_f32_e32 v64, v64, v15
	v_sub_f32_e32 v65, v65, v15
	v_sub_f32_e32 v66, v66, v15
	v_sub_f32_e32 v67, v67, v15
	v_sub_f32_e32 v68, v68, v15
	v_sub_f32_e32 v69, v69, v15
	v_sub_f32_e32 v70, v70, v15
	v_sub_f32_e32 v71, v71, v15
	v_exp_f32_e32 v64, v64
	v_exp_f32_e32 v65, v65
	v_exp_f32_e32 v66, v66
	v_exp_f32_e32 v67, v67
	v_exp_f32_e32 v68, v68
	v_exp_f32_e32 v69, v69
	v_exp_f32_e32 v70, v70
	v_exp_f32_e32 v71, v71
	v_add_f32_e32 v200, v200, v64
	v_add_f32_e32 v200, v200, v65
	v_add_f32_e32 v200, v200, v66
	v_add_f32_e32 v200, v200, v67
	v_add_f32_e32 v200, v200, v68
	v_add_f32_e32 v200, v200, v69
	v_add_f32_e32 v200, v200, v70
	v_add_f32_e32 v200, v200, v71
	v_cvt_pk_bf16_f32 v202, v64, v65
	v_cvt_pk_bf16_f32 v203, v66, v67
	v_cvt_pk_bf16_f32 v204, v68, v69
	v_cvt_pk_bf16_f32 v205, v70, v71
	s_nop 1
	s_waitcnt lgkmcnt(2)
	v_mfma_f32_32x32x16_bf16 v[48:63], v[202:205], v[10:13], v[48:63]
	ds_read_b128 v[10:13], v201 offset:31296
	s_waitcnt lgkmcnt(2)
	v_mfma_f32_32x32x16_bf16 v[32:47], v[202:205], v[2:5], v[32:47]
	ds_read_b128 v[2:5], v201 offset:17504
	s_waitcnt lgkmcnt(2)
	v_mfma_f32_32x32x16_bf16 v[16:31], v[202:205], v[6:9], v[16:31]
	ds_read_b128 v[6:9], v201 offset:22112
	s_waitcnt lgkmcnt(2)
	v_mfma_f32_32x32x16_bf16 v[80:95], v[202:205], v[10:13], v[80:95]
	ds_read_b128 v[10:13], v201 offset:26720
	v_sub_f32_e32 v72, v72, v15
	v_sub_f32_e32 v73, v73, v15
	v_sub_f32_e32 v74, v74, v15
	v_sub_f32_e32 v75, v75, v15
	v_sub_f32_e32 v76, v76, v15
	v_sub_f32_e32 v77, v77, v15
	v_sub_f32_e32 v78, v78, v15
	v_sub_f32_e32 v79, v79, v15
	v_exp_f32_e32 v72, v72
	v_exp_f32_e32 v73, v73
	v_exp_f32_e32 v74, v74
	v_exp_f32_e32 v75, v75
	v_exp_f32_e32 v76, v76
	v_exp_f32_e32 v77, v77
	v_exp_f32_e32 v78, v78
	v_exp_f32_e32 v79, v79
	v_add_f32_e32 v200, v200, v72
	v_add_f32_e32 v200, v200, v73
	v_add_f32_e32 v200, v200, v74
	v_add_f32_e32 v200, v200, v75
	v_add_f32_e32 v200, v200, v76
	v_add_f32_e32 v200, v200, v77
	v_add_f32_e32 v200, v200, v78
	v_add_f32_e32 v200, v200, v79
	v_cvt_pk_bf16_f32 v206, v72, v73
	v_cvt_pk_bf16_f32 v207, v74, v75
	v_cvt_pk_bf16_f32 v208, v76, v77
	v_cvt_pk_bf16_f32 v209, v78, v79
	s_nop 1
	s_waitcnt lgkmcnt(2)
	v_mfma_f32_32x32x16_bf16 v[48:63], v[206:209], v[2:5], v[48:63]
	ds_read_b128 v[2:5], v201 offset:31328
	s_waitcnt lgkmcnt(2)
	v_mfma_f32_32x32x16_bf16 v[32:47], v[206:209], v[6:9], v[32:47]
	s_waitcnt lgkmcnt(1)
	v_mfma_f32_32x32x16_bf16 v[16:31], v[206:209], v[10:13], v[16:31]
	s_waitcnt lgkmcnt(0)
	v_mfma_f32_32x32x16_bf16 v[80:95], v[206:209], v[2:5], v[80:95]
	v_cndmask_b32_e64 v201, v14, 1.0, s[6:7]
	v_fmac_f32_e32 v200, v199, v201
	v_mov_b32_e32 v199, v200
	s_branch .LBB0_1465

; __global__ void __launch_bounds__(NTHREADS) mega_fwd(Args args) {
	.amdhsa_kernel _Z8mega_fwd4Args
		.amdhsa_group_segment_fixed_size 0
		.amdhsa_private_segment_fixed_size 0
		.amdhsa_kernarg_size 488
		.amdhsa_user_sgpr_count 2
		.amdhsa_user_sgpr_dispatch_ptr 0
		.amdhsa_user_sgpr_queue_ptr 0
		.amdhsa_user_sgpr_kernarg_segment_ptr 1
		.amdhsa_user_sgpr_dispatch_id 0
		.amdhsa_user_sgpr_kernarg_preload_length 0
		.amdhsa_user_sgpr_kernarg_preload_offset 0
		.amdhsa_user_sgpr_private_segment_size 0
		.amdhsa_uses_dynamic_stack 0
		.amdhsa_enable_private_segment 0
		.amdhsa_system_sgpr_workgroup_id_x 1
		.amdhsa_system_sgpr_workgroup_id_y 0
		.amdhsa_system_sgpr_workgroup_id_z 0
		.amdhsa_system_sgpr_workgroup_info 0
		.amdhsa_system_vgpr_workitem_id 2
		.amdhsa_next_free_vgpr 256
		.amdhsa_next_free_sgpr 102
		.amdhsa_accum_offset 256
		.amdhsa_reserve_vcc 1
		.amdhsa_float_round_mode_32 0
		.amdhsa_float_round_mode_16_64 0
		.amdhsa_float_denorm_mode_32 3
		.amdhsa_float_denorm_mode_16_64 3
		.amdhsa_dx10_clamp 1
		.amdhsa_ieee_mode 1
		.amdhsa_fp16_overflow 0
		.amdhsa_tg_split 0
		.amdhsa_exception_fp_ieee_invalid_op 0
		.amdhsa_exception_fp_denorm_src 0
		.amdhsa_exception_fp_ieee_div_zero 0
		.amdhsa_exception_fp_ieee_overflow 0
		.amdhsa_exception_fp_ieee_underflow 0
		.amdhsa_exception_fp_ieee_inexact 0
		.amdhsa_exception_int_div_zero 0
	.end_amdhsa_kernel

; __global__ void __launch_bounds__(NTHREADS) mega_fwd(Args args) {
.Lfunc_end0:
	.size	_Z8mega_fwd4Args, .Lfunc_end0-_Z8mega_fwd4Args
	.set _Z8mega_fwd4Args.num_vgpr, 256
	.set _Z8mega_fwd4Args.num_agpr, 0
	.set _Z8mega_fwd4Args.numbered_sgpr, 102
	.set _Z8mega_fwd4Args.num_named_barrier, 0
	.set _Z8mega_fwd4Args.private_seg_size, 0
	.set _Z8mega_fwd4Args.uses_vcc, 1
	.set _Z8mega_fwd4Args.uses_flat_scratch, 0
	.set _Z8mega_fwd4Args.has_dyn_sized_stack, 0
	.set _Z8mega_fwd4Args.has_recursion, 0
	.set _Z8mega_fwd4Args.has_indirect_call, 0

; __global__ void __launch_bounds__(NTHREADS) mega_fwd(Args args) {
amdhsa.kernels:
  - .agpr_count:     0
    .args:
      - .offset:         0
        .size:           232
        .value_kind:     by_value
      - .offset:         232
        .size:           4
        .value_kind:     hidden_block_count_x
      - .offset:         236
        .size:           4
        .value_kind:     hidden_block_count_y
      - .offset:         240
        .size:           4
        .value_kind:     hidden_block_count_z
      - .offset:         244
        .size:           2
        .value_kind:     hidden_group_size_x
      - .offset:         246
        .size:           2
        .value_kind:     hidden_group_size_y
      - .offset:         248
        .size:           2
        .value_kind:     hidden_group_size_z
      - .offset:         250
        .size:           2
        .value_kind:     hidden_remainder_x
      - .offset:         252
        .size:           2
        .value_kind:     hidden_remainder_y
      - .offset:         254
        .size:           2
        .value_kind:     hidden_remainder_z
      - .offset:         272
        .size:           8
        .value_kind:     hidden_global_offset_x
      - .offset:         280
        .size:           8
        .value_kind:     hidden_global_offset_y
      - .offset:         288
        .size:           8
        .value_kind:     hidden_global_offset_z
      - .offset:         296
        .size:           2
        .value_kind:     hidden_grid_dims
      - .offset:         320
        .size:           8
        .value_kind:     hidden_multigrid_sync_arg
      - .offset:         352
        .size:           4
        .value_kind:     hidden_dynamic_lds_size
    .group_segment_fixed_size: 0
    .kernarg_segment_align: 8
    .kernarg_segment_size: 488
    .language:       OpenCL C
    .language_version:
      - 2
      - 0
    .max_flat_workgroup_size: 512
    .name:           _Z8mega_fwd4Args
    .private_segment_fixed_size: 0
    .sgpr_count:     108
    .sgpr_spill_count: 37
    .symbol:         _Z8mega_fwd4Args.kd
    .uniform_work_group_size: 1
    .uses_dynamic_stack: false
    .vgpr_count:     256
    .vgpr_spill_count: 0
    .wavefront_size: 64
